# v19 + row-norm wave sums: xor 1/2/4/8 steps via DPP moves instead of ds_bpermute; phase 0 cache_a conversion: both loads of an iteration issued before the first wait
# speedup vs baseline: 1.0055x; 1.0014x over previous
.LBB0_19:
	s_or_b64 exec, exec, s[16:17]
	v_lshlrev_b32_e32 v84, 16, v140
	v_and_b32_e32 v85, 0xffff0000, v140
	v_pk_mul_f32 v[86:87], v[84:85], v[84:85]
	v_lshlrev_b32_e32 v88, 16, v141
	v_and_b32_e32 v89, 0xffff0000, v141
	v_pk_mul_f32 v[90:91], v[88:89], v[88:89]
	v_add_f32_e32 v83, v86, v87
	v_lshlrev_b32_e32 v92, 16, v138
	v_and_b32_e32 v93, 0xffff0000, v138
	v_add_f32_e32 v83, v90, v83
	v_pk_mul_f32 v[94:95], v[92:93], v[92:93]
	v_add_f32_e32 v83, v91, v83
	v_lshlrev_b32_e32 v96, 16, v139
	v_and_b32_e32 v97, 0xffff0000, v139
	v_add_f32_e32 v83, v94, v83
	v_pk_mul_f32 v[138:139], v[96:97], v[96:97]
	v_add_f32_e32 v83, v95, v83
	v_lshlrev_b32_e32 v140, 16, v136
	v_and_b32_e32 v141, 0xffff0000, v136
	v_add_f32_e32 v83, v138, v83
	v_pk_mul_f32 v[142:143], v[140:141], v[140:141]
	v_add_f32_e32 v83, v139, v83
	v_lshlrev_b32_e32 v136, 16, v137
	v_and_b32_e32 v137, 0xffff0000, v137
	v_add_f32_e32 v83, v142, v83
	v_pk_mul_f32 v[144:145], v[136:137], v[136:137]
	v_add_f32_e32 v83, v143, v83
	v_lshlrev_b32_e32 v148, 16, v134
	v_and_b32_e32 v149, 0xffff0000, v134
	v_add_f32_e32 v83, v144, v83
	v_pk_mul_f32 v[150:151], v[148:149], v[148:149]
	v_add_f32_e32 v83, v145, v83
	v_lshlrev_b32_e32 v134, 16, v135
	v_and_b32_e32 v135, 0xffff0000, v135
	v_add_f32_e32 v83, v150, v83
	v_pk_mul_f32 v[152:153], v[134:135], v[134:135]
	v_add_f32_e32 v83, v151, v83
	v_add_f32_e32 v83, v152, v83
	v_add_f32_e32 v83, v153, v83
	s_nop 1
	v_mov_b32_dpp v86, v83 quad_perm:[1,0,3,2] row_mask:0xf bank_mask:0xf
	v_add_f32_e32 v83, v83, v86
	s_nop 1
	v_mov_b32_dpp v86, v83 quad_perm:[2,3,0,1] row_mask:0xf bank_mask:0xf
	v_add_f32_e32 v83, v83, v86
	s_nop 1
	v_mov_b32_dpp v86, v83 row_half_mirror row_mask:0xf bank_mask:0xf
	v_add_f32_e32 v83, v83, v86
	s_nop 1
	v_mov_b32_dpp v86, v83 row_mirror row_mask:0xf bank_mask:0xf
	v_add_f32_e32 v83, v83, v86
	ds_bpermute_b32 v86, v157, v83
	s_waitcnt lgkmcnt(0)
	v_add_f32_e32 v83, v83, v86
	ds_bpermute_b32 v86, v158, v83
	s_waitcnt lgkmcnt(0)
	v_add_f32_e32 v83, v83, v86
	v_fmamk_f32 v83, v83, 0x3a800000, v207
	v_mul_f32_e32 v86, 0x4b800000, v83
	v_cmp_gt_f32_e32 vcc, s42, v83
	s_nop 1
	v_cndmask_b32_e32 v83, v83, v86, vcc
	v_rsq_f32_e32 v86, v83
	v_ashrrev_i32_e32 v83, 31, v82
	v_lshlrev_b64 v[82:83], 12, v[82:83]
	v_lshl_add_u64 v[82:83], v[106:107], 0, v[82:83]
	v_mul_f32_e32 v87, 0x45800000, v86
	v_cndmask_b32_e32 v86, v86, v87, vcc
	v_pk_mul_f32 v[88:89], v[86:87], v[88:89] op_sel_hi:[0,1]
	v_pk_mul_f32 v[84:85], v[86:87], v[84:85] op_sel_hi:[0,1]
	v_pk_mul_f32 v[84:85], v[10:11], v[84:85]
	v_pk_mul_f32 v[88:89], v[12:13], v[88:89]
	s_waitcnt vmcnt(3)
	v_pk_fma_f32 v[50:51], v[66:67], v[84:85], v[50:51]
	v_pk_fma_f32 v[52:53], v[68:69], v[88:89], v[52:53]
	global_store_dwordx4 v[82:83], v[50:53], off nt
	s_nop 1
	v_pk_mul_f32 v[50:51], v[86:87], v[96:97] op_sel_hi:[0,1]
	v_pk_mul_f32 v[52:53], v[86:87], v[92:93] op_sel_hi:[0,1]
	v_pk_mul_f32 v[52:53], v[2:3], v[52:53]
	v_pk_mul_f32 v[50:51], v[4:5], v[50:51]
	s_waitcnt vmcnt(3)
	v_pk_fma_f32 v[26:27], v[70:71], v[52:53], v[26:27]
	v_pk_fma_f32 v[28:29], v[72:73], v[50:51], v[28:29]
	global_store_dwordx4 v[82:83], v[26:29], off offset:1024 nt
	s_nop 1
	v_pk_mul_f32 v[26:27], v[86:87], v[136:137] op_sel_hi:[0,1]
	v_pk_mul_f32 v[28:29], v[86:87], v[140:141] op_sel_hi:[0,1]
	v_pk_mul_f32 v[28:29], v[6:7], v[28:29]
	v_pk_mul_f32 v[26:27], v[8:9], v[26:27]
	s_waitcnt vmcnt(3)
	v_pk_fma_f32 v[22:23], v[74:75], v[28:29], v[22:23]
	v_pk_fma_f32 v[24:25], v[76:77], v[26:27], v[24:25]
	global_store_dwordx4 v[82:83], v[22:25], off offset:2048 nt
	s_nop 1
	v_pk_mul_f32 v[22:23], v[86:87], v[134:135] op_sel_hi:[0,1]
	v_pk_mul_f32 v[24:25], v[86:87], v[148:149] op_sel_hi:[0,1]
	v_pk_mul_f32 v[24:25], v[14:15], v[24:25]
	v_pk_mul_f32 v[22:23], v[16:17], v[22:23]
	s_waitcnt vmcnt(3)
	v_pk_fma_f32 v[18:19], v[78:79], v[24:25], v[18:19]
	v_pk_fma_f32 v[20:21], v[80:81], v[22:23], v[20:21]
	global_store_dwordx4 v[82:83], v[18:21], off offset:3072 nt

.LBB0_27:
	s_or_b64 exec, exec, s[14:15]
	s_waitcnt vmcnt(3)
	v_lshlrev_b32_e32 v152, 16, v150
	v_and_b32_e32 v153, 0xffff0000, v150
	v_pk_mul_f32 v[160:161], v[152:153], v[152:153]
	v_lshlrev_b32_e32 v150, 16, v151
	v_and_b32_e32 v151, 0xffff0000, v151
	v_pk_mul_f32 v[162:163], v[150:151], v[150:151]
	v_add_f32_e32 v99, v160, v161
	s_waitcnt vmcnt(2)
	v_lshlrev_b32_e32 v164, 16, v148
	v_and_b32_e32 v165, 0xffff0000, v148
	v_add_f32_e32 v99, v162, v99
	v_pk_mul_f32 v[166:167], v[164:165], v[164:165]
	v_add_f32_e32 v99, v163, v99
	v_lshlrev_b32_e32 v148, 16, v149
	v_and_b32_e32 v149, 0xffff0000, v149
	v_add_f32_e32 v99, v166, v99
	v_pk_mul_f32 v[168:169], v[148:149], v[148:149]
	v_add_f32_e32 v99, v167, v99
	s_waitcnt vmcnt(1)
	v_lshlrev_b32_e32 v170, 16, v144
	v_and_b32_e32 v171, 0xffff0000, v144
	v_add_f32_e32 v99, v168, v99
	v_pk_mul_f32 v[172:173], v[170:171], v[170:171]
	v_add_f32_e32 v99, v169, v99
	v_lshlrev_b32_e32 v144, 16, v145
	v_and_b32_e32 v145, 0xffff0000, v145
	v_add_f32_e32 v99, v172, v99
	v_pk_mul_f32 v[174:175], v[144:145], v[144:145]
	v_add_f32_e32 v99, v173, v99
	s_waitcnt vmcnt(0)
	v_lshlrev_b32_e32 v176, 16, v142
	v_and_b32_e32 v177, 0xffff0000, v142
	v_add_f32_e32 v99, v174, v99
	v_pk_mul_f32 v[178:179], v[176:177], v[176:177]
	v_add_f32_e32 v99, v175, v99
	v_lshlrev_b32_e32 v142, 16, v143
	v_and_b32_e32 v143, 0xffff0000, v143
	v_add_f32_e32 v99, v178, v99
	v_pk_mul_f32 v[180:181], v[142:143], v[142:143]
	v_add_f32_e32 v99, v179, v99
	v_add_f32_e32 v99, v180, v99
	v_add_f32_e32 v99, v181, v99
	s_nop 1
	v_mov_b32_dpp v103, v99 quad_perm:[1,0,3,2] row_mask:0xf bank_mask:0xf
	v_lshl_add_u64 v[160:161], v[112:113], 0, v[110:111]
	s_waitcnt lgkmcnt(0)
	v_add_f32_e32 v99, v99, v103
	s_nop 1
	v_mov_b32_dpp v103, v99 quad_perm:[2,3,0,1] row_mask:0xf bank_mask:0xf
	s_waitcnt lgkmcnt(0)
	v_add_f32_e32 v99, v99, v103
	s_nop 1
	v_mov_b32_dpp v103, v99 row_half_mirror row_mask:0xf bank_mask:0xf
	s_waitcnt lgkmcnt(0)
	v_add_f32_e32 v99, v99, v103
	s_nop 1
	v_mov_b32_dpp v103, v99 row_mirror row_mask:0xf bank_mask:0xf
	s_waitcnt lgkmcnt(0)
	v_add_f32_e32 v99, v99, v103
	ds_bpermute_b32 v103, v157, v99
	s_waitcnt lgkmcnt(0)
	v_add_f32_e32 v99, v99, v103
	ds_bpermute_b32 v103, v158, v99
	s_waitcnt lgkmcnt(0)
	v_add_f32_e32 v99, v99, v103
	v_fmamk_f32 v99, v99, 0x3a800000, v207
	v_mul_f32_e32 v103, 0x4b800000, v99
	v_cmp_gt_f32_e32 vcc, s42, v99
	s_nop 1
	v_cndmask_b32_e32 v99, v99, v103, vcc
	v_rsq_f32_e32 v99, v99
	s_nop 0
	v_mul_f32_e32 v103, 0x45800000, v99
	v_cndmask_b32_e32 v162, v99, v103, vcc
	v_pk_mul_f32 v[150:151], v[162:163], v[150:151] op_sel_hi:[0,1]
	v_pk_mul_f32 v[152:153], v[162:163], v[152:153] op_sel_hi:[0,1]
	v_pk_mul_f32 v[152:153], v[10:11], v[152:153]
	v_pk_mul_f32 v[150:151], v[12:13], v[150:151]
	v_pk_fma_f32 v[94:95], v[66:67], v[152:153], v[94:95]
	v_pk_fma_f32 v[96:97], v[68:69], v[150:151], v[96:97]
	global_store_dwordx4 v[160:161], v[94:97], off nt
	s_nop 1
	v_pk_mul_f32 v[94:95], v[162:163], v[148:149] op_sel_hi:[0,1]
	v_pk_mul_f32 v[96:97], v[162:163], v[164:165] op_sel_hi:[0,1]
	v_pk_mul_f32 v[96:97], v[2:3], v[96:97]
	v_pk_mul_f32 v[94:95], v[4:5], v[94:95]
	v_pk_fma_f32 v[90:91], v[70:71], v[96:97], v[90:91]
	v_pk_fma_f32 v[92:93], v[72:73], v[94:95], v[92:93]
	global_store_dwordx4 v[160:161], v[90:93], off offset:1024 nt
	s_nop 1
	v_pk_mul_f32 v[90:91], v[162:163], v[144:145] op_sel_hi:[0,1]
	v_pk_mul_f32 v[92:93], v[162:163], v[170:171] op_sel_hi:[0,1]
	v_pk_mul_f32 v[92:93], v[6:7], v[92:93]
	v_pk_mul_f32 v[90:91], v[8:9], v[90:91]
	v_pk_fma_f32 v[86:87], v[74:75], v[92:93], v[86:87]
	v_pk_fma_f32 v[88:89], v[76:77], v[90:91], v[88:89]
	global_store_dwordx4 v[160:161], v[86:89], off offset:2048 nt
	s_nop 1
	v_pk_mul_f32 v[86:87], v[162:163], v[142:143] op_sel_hi:[0,1]
	v_pk_mul_f32 v[88:89], v[162:163], v[176:177] op_sel_hi:[0,1]
	v_pk_mul_f32 v[88:89], v[14:15], v[88:89]
	v_pk_mul_f32 v[86:87], v[16:17], v[86:87]
	v_pk_fma_f32 v[82:83], v[78:79], v[88:89], v[82:83]
	v_pk_fma_f32 v[84:85], v[80:81], v[86:87], v[84:85]
	global_store_dwordx4 v[160:161], v[82:85], off offset:3072 nt
	s_nop 1
	v_add_u32_e32 v82, s1, v98
	v_cmp_gt_i32_e32 vcc, s7, v82
	s_and_saveexec_b64 s[14:15], vcc
	s_cbranch_execz .LBB0_20
	v_add_u32_e32 v83, 0xffffe000, v82
	v_ashrrev_i32_e32 v83, 12, v83
	v_add_u32_e32 v83, 1, v83
	v_cmp_lt_i32_e32 vcc, s43, v82
	s_nop 1
	v_cndmask_b32_e32 v83, 0, v83, vcc
	v_cmp_ne_u32_e32 vcc, v83, v101
	s_and_saveexec_b64 s[16:17], vcc
	s_cbranch_execz .LBB0_19
	v_mul_i32_i24_e32 v66, 0xc00, v83
	v_ashrrev_i32_e32 v67, 31, v66
	v_lshl_add_u64 v[66:67], v[66:67], 2, s[62:63]
	v_lshl_add_u64 v[74:75], v[66:67], 0, s[22:23]
	v_mov_b32_e32 v101, v1
	v_mov_b32_e32 v103, v1
	v_mov_b32_e32 v105, v1
	v_lshl_add_u64 v[66:67], v[74:75], 0, v[0:1]
	v_lshl_add_u64 v[70:71], v[74:75], 0, v[100:101]
	v_lshl_add_u64 v[76:77], v[74:75], 0, v[102:103]
	v_lshl_add_u64 v[78:79], v[74:75], 0, v[104:105]
	global_load_dwordx4 v[66:69], v[66:67], off
	s_nop 0
	global_load_dwordx4 v[70:73], v[70:71], off
	s_nop 0
	global_load_dwordx4 v[74:77], v[76:77], off
	s_nop 0
	global_load_dwordx4 v[78:81], v[78:79], off
	v_mov_b32_e32 v101, v83
	s_branch .LBB0_19

.LBB0_750:
	s_or_b64 exec, exec, s[18:19]
	v_lshlrev_b32_e32 v198, 16, v184
	v_and_b32_e32 v199, 0xffff0000, v184
	v_pk_mul_f32 v[200:201], v[198:199], v[198:199]
	v_lshlrev_b32_e32 v184, 16, v185
	v_and_b32_e32 v185, 0xffff0000, v185
	v_pk_mul_f32 v[202:203], v[184:185], v[184:185]
	v_add_f32_e32 v131, v200, v201
	v_lshlrev_b32_e32 v204, 16, v180
	v_and_b32_e32 v205, 0xffff0000, v180
	v_add_f32_e32 v131, v202, v131
	v_pk_mul_f32 v[218:219], v[204:205], v[204:205]
	v_add_f32_e32 v131, v203, v131
	v_lshlrev_b32_e32 v180, 16, v181
	v_and_b32_e32 v181, 0xffff0000, v181
	v_add_f32_e32 v131, v218, v131
	v_pk_mul_f32 v[220:221], v[180:181], v[180:181]
	v_add_f32_e32 v131, v219, v131
	v_lshlrev_b32_e32 v222, 16, v170
	v_and_b32_e32 v223, 0xffff0000, v170
	v_add_f32_e32 v131, v220, v131
	v_pk_mul_f32 v[236:237], v[222:223], v[222:223]
	v_add_f32_e32 v131, v221, v131
	v_lshlrev_b32_e32 v170, 16, v171
	v_and_b32_e32 v171, 0xffff0000, v171
	v_add_f32_e32 v131, v236, v131
	v_pk_mul_f32 v[238:239], v[170:171], v[170:171]
	v_add_f32_e32 v131, v237, v131
	v_lshlrev_b32_e32 v240, 16, v168
	v_and_b32_e32 v241, 0xffff0000, v168
	v_add_f32_e32 v131, v238, v131
	v_pk_mul_f32 v[242:243], v[240:241], v[240:241]
	v_add_f32_e32 v131, v239, v131
	v_lshlrev_b32_e32 v168, 16, v169
	v_and_b32_e32 v169, 0xffff0000, v169
	v_add_f32_e32 v131, v242, v131
	v_pk_mul_f32 v[244:245], v[168:169], v[168:169]
	v_add_f32_e32 v131, v243, v131
	v_add_f32_e32 v131, v244, v131
	v_add_f32_e32 v131, v245, v131
	s_nop 1
	v_mov_b32_dpp v151, v131 quad_perm:[1,0,3,2] row_mask:0xf bank_mask:0xf
	v_add_f32_e32 v131, v131, v151
	s_nop 1
	v_mov_b32_dpp v151, v131 quad_perm:[2,3,0,1] row_mask:0xf bank_mask:0xf
	v_add_f32_e32 v131, v131, v151
	s_nop 1
	v_mov_b32_dpp v151, v131 row_half_mirror row_mask:0xf bank_mask:0xf
	v_add_f32_e32 v131, v131, v151
	s_nop 1
	v_mov_b32_dpp v151, v131 row_mirror row_mask:0xf bank_mask:0xf
	v_add_f32_e32 v131, v131, v151
	ds_bpermute_b32 v151, v234, v131
	s_waitcnt lgkmcnt(0)
	v_add_f32_e32 v131, v131, v151
	ds_bpermute_b32 v151, v235, v131
	s_waitcnt lgkmcnt(0)
	v_add_f32_e32 v131, v131, v151
	v_fmamk_f32 v131, v131, 0x3a800000, v207
	v_mul_f32_e32 v151, 0x4b800000, v131
	v_cmp_gt_f32_e32 vcc, s42, v131
	s_nop 1
	v_cndmask_b32_e32 v131, v131, v151, vcc
	v_rsq_f32_e32 v131, v131
	s_nop 0
	v_mul_f32_e32 v151, 0x45800000, v131
	v_cndmask_b32_e32 v194, v131, v151, vcc
	v_pk_mul_f32 v[198:199], v[194:195], v[198:199] op_sel_hi:[0,1]
	v_pk_mul_f32 v[170:171], v[194:195], v[170:171] op_sel_hi:[0,1]
	v_pk_mul_f32 v[184:185], v[194:195], v[184:185] op_sel_hi:[0,1]
	v_pk_mul_f32 v[198:199], v[2:3], v[198:199]
	v_pk_mul_f32 v[170:171], v[20:21], v[170:171]
	v_pk_mul_f32 v[168:169], v[194:195], v[168:169] op_sel_hi:[0,1]
	v_pk_mul_f32 v[184:185], v[4:5], v[184:185]
	v_pk_fma_f32 v[46:47], v[50:51], v[198:199], v[46:47]
	v_pk_mul_f32 v[180:181], v[194:195], v[180:181] op_sel_hi:[0,1]
	s_waitcnt vmcnt(2)
	v_pk_fma_f32 v[40:41], v[112:113], v[170:171], v[40:41]
	v_pk_mul_f32 v[170:171], v[194:195], v[240:241] op_sel_hi:[0,1]
	v_pk_mul_f32 v[168:169], v[24:25], v[168:169]
	v_pk_mul_f32 v[200:201], v[194:195], v[204:205] op_sel_hi:[0,1]
	v_pk_fma_f32 v[48:49], v[52:53], v[184:185], v[48:49]
	v_pk_mul_f32 v[180:181], v[8:9], v[180:181]
	v_pk_mul_f32 v[170:171], v[22:23], v[170:171]
	s_waitcnt vmcnt(0)
	v_pk_fma_f32 v[36:37], v[120:121], v[168:169], v[36:37]
	v_pk_mul_f32 v[168:169], v[46:47], v[46:47]
	v_pk_mul_f32 v[184:185], v[6:7], v[200:201]
	v_pk_fma_f32 v[44:45], v[76:77], v[180:181], v[44:45]
	v_pk_mul_f32 v[180:181], v[194:195], v[222:223] op_sel_hi:[0,1]
	v_pk_fma_f32 v[34:35], v[118:119], v[170:171], v[34:35]
	v_pk_mul_f32 v[170:171], v[48:49], v[48:49]
	v_add_f32_e32 v131, v168, v169
	v_pk_fma_f32 v[42:43], v[74:75], v[184:185], v[42:43]
	v_pk_mul_f32 v[180:181], v[18:19], v[180:181]
	v_add_f32_e32 v131, v170, v131
	v_pk_fma_f32 v[38:39], v[110:111], v[180:181], v[38:39]
	v_pk_mul_f32 v[180:181], v[42:43], v[42:43]
	v_add_f32_e32 v131, v171, v131
	v_add_f32_e32 v131, v180, v131
	v_pk_mul_f32 v[184:185], v[44:45], v[44:45]
	v_add_f32_e32 v131, v181, v131
	v_add_f32_e32 v131, v184, v131
	v_pk_mul_f32 v[198:199], v[38:39], v[38:39]
	v_add_f32_e32 v131, v185, v131
	v_add_f32_e32 v131, v198, v131
	v_pk_mul_f32 v[200:201], v[40:41], v[40:41]
	v_add_f32_e32 v131, v199, v131
	v_add_f32_e32 v131, v200, v131
	v_pk_mul_f32 v[202:203], v[34:35], v[34:35]
	v_add_f32_e32 v131, v201, v131
	v_add_f32_e32 v131, v202, v131
	v_pk_mul_f32 v[204:205], v[36:37], v[36:37]
	v_add_f32_e32 v131, v203, v131
	v_add_f32_e32 v131, v204, v131
	v_add_f32_e32 v131, v205, v131
	ds_bpermute_b32 v151, v147, v131
	s_waitcnt lgkmcnt(0)
	v_add_f32_e32 v131, v131, v151
	ds_bpermute_b32 v151, v195, v131
	s_waitcnt lgkmcnt(0)
	v_add_f32_e32 v131, v131, v151
	ds_bpermute_b32 v151, v232, v131
	s_waitcnt lgkmcnt(0)
	v_add_f32_e32 v131, v131, v151
	ds_bpermute_b32 v151, v233, v131
	s_waitcnt lgkmcnt(0)
	v_add_f32_e32 v131, v131, v151
	ds_bpermute_b32 v151, v234, v131
	s_waitcnt lgkmcnt(0)
	v_add_f32_e32 v151, v131, v151
	ds_bpermute_b32 v153, v235, v151
	v_ashrrev_i32_e32 v131, 31, v130
	v_lshlrev_b64 v[168:169], 12, v[130:131]
	v_lshl_add_u64 v[168:169], v[156:157], 0, v[168:169]
	global_store_dwordx4 v[168:169], v[46:49], off nt
	s_waitcnt lgkmcnt(0)
	v_add_f32_e32 v151, v151, v153
	v_fmamk_f32 v151, v151, 0x3a800000, v207
	v_mul_f32_e32 v153, 0x4b800000, v151
	v_cmp_gt_f32_e32 vcc, s42, v151
	global_store_dwordx4 v[168:169], v[42:45], off offset:1024 nt
	global_store_dwordx4 v[168:169], v[38:41], off offset:2048 nt
	global_store_dwordx4 v[168:169], v[34:37], off offset:3072 nt
	v_cndmask_b32_e32 v151, v151, v153, vcc
	v_rsq_f32_e32 v151, v151
	s_nop 0
	v_mul_f32_e32 v153, 0x45800000, v151
	v_cndmask_b32_e32 v168, v151, v153, vcc
	v_pk_mul_f32 v[46:47], v[46:47], v[168:169] op_sel_hi:[1,0]
	v_pk_mul_f32 v[48:49], v[48:49], v[168:169] op_sel_hi:[1,0]
	v_pk_mul_f32 v[46:47], v[26:27], v[46:47]
	v_pk_mul_f32 v[48:49], v[28:29], v[48:49]
	v_pk_mul_f32 v[42:43], v[42:43], v[168:169] op_sel_hi:[1,0]
	v_pk_mul_f32 v[44:45], v[44:45], v[168:169] op_sel_hi:[1,0]
	v_pk_mul_f32 v[38:39], v[38:39], v[168:169] op_sel_hi:[1,0]
	v_pk_mul_f32 v[40:41], v[40:41], v[168:169] op_sel_hi:[1,0]
	v_pk_mul_f32 v[34:35], v[34:35], v[168:169] op_sel_hi:[1,0]
	v_pk_mul_f32 v[36:37], v[36:37], v[168:169] op_sel_hi:[1,0]
	v_pk_fma_f32 v[46:47], v[132:133], v[46:47], v[70:71]
	v_pk_fma_f32 v[48:49], v[134:135], v[48:49], v[72:73]
	v_pk_mul_f32 v[42:43], v[10:11], v[42:43]
	v_pk_mul_f32 v[44:45], v[12:13], v[44:45]
	v_pk_mul_f32 v[38:39], v[14:15], v[38:39]
	v_pk_mul_f32 v[40:41], v[16:17], v[40:41]
	v_pk_mul_f32 v[34:35], v[30:31], v[34:35]
	v_pk_mul_f32 v[36:37], v[32:33], v[36:37]
	v_cvt_pk_bf16_f32 v46, v46, v47
	v_cvt_pk_bf16_f32 v47, v48, v49
	v_lshlrev_b64 v[48:49], 11, v[130:131]
	v_pk_fma_f32 v[42:43], v[136:137], v[42:43], v[102:103]
	v_pk_fma_f32 v[44:45], v[138:139], v[44:45], v[104:105]
	v_pk_fma_f32 v[38:39], v[140:141], v[38:39], v[114:115]
	v_pk_fma_f32 v[40:41], v[142:143], v[40:41], v[116:117]
	v_pk_fma_f32 v[34:35], v[144:145], v[34:35], v[126:127]
	v_pk_fma_f32 v[36:37], v[196:197], v[36:37], v[128:129]
	v_lshl_add_u64 v[48:49], v[158:159], 0, v[48:49]
	v_cvt_pk_bf16_f32 v42, v42, v43
	v_cvt_pk_bf16_f32 v43, v44, v45
	v_cvt_pk_bf16_f32 v38, v38, v39
	v_cvt_pk_bf16_f32 v39, v40, v41
	v_cvt_pk_bf16_f32 v34, v34, v35
	v_cvt_pk_bf16_f32 v35, v36, v37
	global_store_dwordx2 v[48:49], v[46:47], off
	global_store_dwordx2 v[48:49], v[42:43], off offset:512
	global_store_dwordx2 v[48:49], v[38:39], off offset:1024
	global_store_dwordx2 v[48:49], v[34:35], off offset:1536

.LBB0_766:
	s_or_b64 exec, exec, s[0:1]
	s_waitcnt vmcnt(3)
	v_lshlrev_b32_e32 v204, 16, v202
	v_and_b32_e32 v205, 0xffff0000, v202
	v_pk_mul_f32 v[236:237], v[204:205], v[204:205]
	v_lshlrev_b32_e32 v202, 16, v203
	v_and_b32_e32 v203, 0xffff0000, v203
	v_pk_mul_f32 v[238:239], v[202:203], v[202:203]
	v_add_f32_e32 v151, v236, v237
	s_waitcnt vmcnt(2)
	v_lshlrev_b32_e32 v240, 16, v200
	v_and_b32_e32 v241, 0xffff0000, v200
	v_add_f32_e32 v151, v238, v151
	v_pk_mul_f32 v[242:243], v[240:241], v[240:241]
	v_add_f32_e32 v151, v239, v151
	v_lshlrev_b32_e32 v200, 16, v201
	v_and_b32_e32 v201, 0xffff0000, v201
	v_add_f32_e32 v151, v242, v151
	v_pk_mul_f32 v[244:245], v[200:201], v[200:201]
	v_add_f32_e32 v151, v243, v151
	s_waitcnt vmcnt(1)
	v_lshlrev_b32_e32 v246, 16, v198
	v_and_b32_e32 v247, 0xffff0000, v198
	v_add_f32_e32 v151, v244, v151
	v_pk_mul_f32 v[248:249], v[246:247], v[246:247]
	v_add_f32_e32 v151, v245, v151
	v_lshlrev_b32_e32 v250, 16, v199
	v_and_b32_e32 v251, 0xffff0000, v199
	v_add_f32_e32 v151, v248, v151
	v_pk_mul_f32 v[198:199], v[250:251], v[250:251]
	v_add_f32_e32 v151, v249, v151
	s_waitcnt vmcnt(0)
	v_lshlrev_b32_e32 v218, 16, v196
	v_and_b32_e32 v219, 0xffff0000, v196
	v_add_f32_e32 v151, v198, v151
	v_pk_mul_f32 v[220:221], v[218:219], v[218:219]
	v_add_f32_e32 v151, v199, v151
	v_lshlrev_b32_e32 v222, 16, v197
	v_and_b32_e32 v223, 0xffff0000, v197
	v_add_f32_e32 v151, v220, v151
	v_pk_mul_f32 v[196:197], v[222:223], v[222:223]
	v_add_f32_e32 v151, v221, v151
	v_add_f32_e32 v151, v196, v151
	v_add_f32_e32 v151, v197, v151
	s_nop 1
	v_mov_b32_dpp v153, v151 quad_perm:[1,0,3,2] row_mask:0xf bank_mask:0xf
	s_movk_i32 s0, 0x6000
	s_waitcnt lgkmcnt(0)
	v_add_f32_e32 v151, v151, v153
	s_nop 1
	v_mov_b32_dpp v153, v151 quad_perm:[2,3,0,1] row_mask:0xf bank_mask:0xf
	s_waitcnt lgkmcnt(0)
	v_add_f32_e32 v151, v151, v153
	s_nop 1
	v_mov_b32_dpp v153, v151 row_half_mirror row_mask:0xf bank_mask:0xf
	s_waitcnt lgkmcnt(0)
	v_add_f32_e32 v151, v151, v153
	s_nop 1
	v_mov_b32_dpp v153, v151 row_mirror row_mask:0xf bank_mask:0xf
	s_waitcnt lgkmcnt(0)
	v_add_f32_e32 v151, v151, v153
	ds_bpermute_b32 v153, v234, v151
	s_waitcnt lgkmcnt(0)
	v_add_f32_e32 v151, v151, v153
	ds_bpermute_b32 v153, v235, v151
	s_waitcnt lgkmcnt(0)
	v_add_f32_e32 v151, v151, v153
	v_fmamk_f32 v151, v151, 0x3a800000, v207
	v_mul_f32_e32 v153, 0x4b800000, v151
	v_cmp_gt_f32_e32 vcc, s42, v151
	s_nop 1
	v_cndmask_b32_e32 v151, v151, v153, vcc
	v_rsq_f32_e32 v151, v151
	s_nop 0
	v_mul_f32_e32 v153, 0x45800000, v151
	v_cndmask_b32_e32 v220, v151, v153, vcc
	v_pk_mul_f32 v[196:197], v[220:221], v[204:205] op_sel_hi:[0,1]
	v_pk_mul_f32 v[198:199], v[220:221], v[202:203] op_sel_hi:[0,1]
	v_pk_mul_f32 v[202:203], v[220:221], v[240:241] op_sel_hi:[0,1]
	v_pk_mul_f32 v[196:197], v[2:3], v[196:197]
	v_pk_mul_f32 v[198:199], v[4:5], v[198:199]
	v_pk_fma_f32 v[142:143], v[50:51], v[196:197], v[142:143]
	v_pk_mul_f32 v[196:197], v[6:7], v[202:203]
	v_pk_fma_f32 v[144:145], v[52:53], v[198:199], v[144:145]
	v_pk_fma_f32 v[196:197], v[74:75], v[196:197], v[138:139]
	v_pk_mul_f32 v[138:139], v[220:221], v[200:201] op_sel_hi:[0,1]
	v_pk_mul_f32 v[138:139], v[8:9], v[138:139]
	s_nop 0
	v_pk_fma_f32 v[198:199], v[76:77], v[138:139], v[140:141]
	v_pk_mul_f32 v[138:139], v[220:221], v[246:247] op_sel_hi:[0,1]
	v_pk_mul_f32 v[138:139], v[18:19], v[138:139]
	s_nop 0
	v_pk_fma_f32 v[200:201], v[110:111], v[138:139], v[134:135]
	v_pk_mul_f32 v[134:135], v[220:221], v[250:251] op_sel_hi:[0,1]
	v_pk_mul_f32 v[134:135], v[20:21], v[134:135]
	v_pk_mul_f32 v[138:139], v[200:201], v[200:201]
	v_pk_fma_f32 v[202:203], v[112:113], v[134:135], v[136:137]
	v_pk_mul_f32 v[134:135], v[220:221], v[218:219] op_sel_hi:[0,1]
	v_pk_mul_f32 v[134:135], v[22:23], v[134:135]
	v_pk_mul_f32 v[136:137], v[198:199], v[198:199]
	v_pk_fma_f32 v[236:237], v[118:119], v[134:135], v[130:131]
	v_pk_mul_f32 v[130:131], v[220:221], v[222:223] op_sel_hi:[0,1]
	v_pk_mul_f32 v[130:131], v[24:25], v[130:131]
	v_pk_mul_f32 v[134:135], v[196:197], v[196:197]
	v_pk_fma_f32 v[238:239], v[120:121], v[130:131], v[132:133]
	v_pk_mul_f32 v[130:131], v[142:143], v[142:143]
	v_pk_mul_f32 v[132:133], v[144:145], v[144:145]
	v_add_f32_e32 v130, v130, v131
	v_add_f32_e32 v130, v132, v130
	v_add_f32_e32 v130, v133, v130
	v_add_f32_e32 v130, v134, v130
	v_add_f32_e32 v130, v135, v130
	v_add_f32_e32 v130, v136, v130
	v_add_f32_e32 v130, v137, v130
	v_add_f32_e32 v130, v138, v130
	v_pk_mul_f32 v[140:141], v[202:203], v[202:203]
	v_add_f32_e32 v130, v139, v130
	v_add_f32_e32 v130, v140, v130
	v_pk_mul_f32 v[204:205], v[236:237], v[236:237]
	v_add_f32_e32 v130, v141, v130
	v_add_f32_e32 v130, v204, v130
	v_pk_mul_f32 v[218:219], v[238:239], v[238:239]
	v_add_f32_e32 v130, v205, v130
	v_add_f32_e32 v130, v218, v130
	v_add_f32_e32 v130, v219, v130
	ds_bpermute_b32 v131, v147, v130
	v_pk_add_f32 v[134:135], v[80:81], 1.0 op_sel_hi:[1,0]
	s_waitcnt lgkmcnt(0)
	v_add_f32_e32 v130, v130, v131
	ds_bpermute_b32 v131, v195, v130
	s_waitcnt lgkmcnt(0)
	v_add_f32_e32 v130, v130, v131
	ds_bpermute_b32 v131, v232, v130
	s_waitcnt lgkmcnt(0)
	v_add_f32_e32 v130, v130, v131
	ds_bpermute_b32 v131, v233, v130
	s_waitcnt lgkmcnt(0)
	v_add_f32_e32 v130, v130, v131
	ds_bpermute_b32 v131, v234, v130
	s_waitcnt lgkmcnt(0)
	v_add_f32_e32 v132, v130, v131
	ds_bpermute_b32 v133, v235, v132
	v_lshl_add_u64 v[130:131], v[166:167], 0, s[16:17]
	global_store_dwordx4 v[130:131], v[142:145], off nt
	global_store_dwordx4 v[130:131], v[196:199], off offset:1024 nt
	global_store_dwordx4 v[130:131], v[200:203], off offset:2048 nt
	global_store_dwordx4 v[130:131], v[236:239], off offset:3072 nt
	s_waitcnt lgkmcnt(0)
	v_add_f32_e32 v132, v132, v133
	v_fmamk_f32 v132, v132, 0x3a800000, v207
	v_mul_f32_e32 v133, 0x4b800000, v132
	v_cmp_gt_f32_e32 vcc, s42, v132
	s_nop 1
	v_cndmask_b32_e32 v132, v132, v133, vcc
	v_rsq_f32_e32 v132, v132
	s_nop 0
	v_mul_f32_e32 v130, 0x45800000, v132
	v_cndmask_b32_e32 v130, v132, v130, vcc
	v_pk_mul_f32 v[136:137], v[142:143], v[130:131] op_sel_hi:[1,0]
	v_pk_mul_f32 v[138:139], v[144:145], v[130:131] op_sel_hi:[1,0]
	v_pk_add_f32 v[132:133], v[78:79], 1.0 op_sel_hi:[1,0]
	v_pk_mul_f32 v[136:137], v[26:27], v[136:137]
	v_pk_mul_f32 v[138:139], v[28:29], v[138:139]
	v_pk_fma_f32 v[136:137], v[132:133], v[136:137], v[70:71]
	v_pk_fma_f32 v[138:139], v[134:135], v[138:139], v[72:73]
	v_cvt_pk_bf16_f32 v136, v136, v137
	v_cvt_pk_bf16_f32 v137, v138, v139
	v_pk_mul_f32 v[140:141], v[196:197], v[130:131] op_sel_hi:[1,0]
	v_pk_mul_f32 v[142:143], v[198:199], v[130:131] op_sel_hi:[1,0]
	global_store_dwordx2 v[160:161], v[136:137], off offset:-1024
	v_pk_add_f32 v[136:137], v[98:99], 1.0 op_sel_hi:[1,0]
	v_pk_add_f32 v[138:139], v[100:101], 1.0 op_sel_hi:[1,0]
	v_pk_mul_f32 v[140:141], v[10:11], v[140:141]
	v_pk_mul_f32 v[142:143], v[12:13], v[142:143]
	v_pk_fma_f32 v[140:141], v[136:137], v[140:141], v[102:103]
	v_pk_fma_f32 v[142:143], v[138:139], v[142:143], v[104:105]
	v_cvt_pk_bf16_f32 v140, v140, v141
	v_cvt_pk_bf16_f32 v141, v142, v143
	v_pk_mul_f32 v[144:145], v[200:201], v[130:131] op_sel_hi:[1,0]
	v_pk_mul_f32 v[196:197], v[202:203], v[130:131] op_sel_hi:[1,0]
	global_store_dwordx2 v[160:161], v[140:141], off offset:-512
	v_pk_add_f32 v[140:141], v[106:107], 1.0 op_sel_hi:[1,0]
	v_pk_add_f32 v[142:143], v[108:109], 1.0 op_sel_hi:[1,0]
	v_pk_mul_f32 v[144:145], v[14:15], v[144:145]
	v_pk_mul_f32 v[196:197], v[16:17], v[196:197]
	v_pk_fma_f32 v[144:145], v[140:141], v[144:145], v[114:115]
	v_pk_fma_f32 v[196:197], v[142:143], v[196:197], v[116:117]
	v_cvt_pk_bf16_f32 v144, v144, v145
	v_cvt_pk_bf16_f32 v145, v196, v197
	v_pk_mul_f32 v[198:199], v[236:237], v[130:131] op_sel_hi:[1,0]
	v_pk_mul_f32 v[130:131], v[238:239], v[130:131] op_sel_hi:[1,0]
	global_store_dwordx2 v[160:161], v[144:145], off
	v_pk_add_f32 v[144:145], v[122:123], 1.0 op_sel_hi:[1,0]
	v_pk_add_f32 v[196:197], v[124:125], 1.0 op_sel_hi:[1,0]
	v_pk_mul_f32 v[198:199], v[30:31], v[198:199]
	v_pk_mul_f32 v[130:131], v[32:33], v[130:131]
	v_pk_fma_f32 v[198:199], v[144:145], v[198:199], v[126:127]
	v_pk_fma_f32 v[130:131], v[196:197], v[130:131], v[128:129]
	v_cvt_pk_bf16_f32 v198, v198, v199
	v_cvt_pk_bf16_f32 v199, v130, v131
	v_add_u32_e32 v130, s3, v194
	v_cmp_gt_i32_e32 vcc, s0, v130
	global_store_dwordx2 v[160:161], v[198:199], off offset:512
	s_and_saveexec_b64 s[0:1], vcc
	s_cbranch_execz .LBB0_751
	v_add_u32_e32 v131, 0xffffe000, v130
	v_ashrrev_i32_e32 v131, 12, v131
	v_add_u32_e32 v131, 1, v131
	v_cmp_lt_i32_e32 vcc, s43, v130
	s_nop 1
	v_cndmask_b32_e32 v131, 0, v131, vcc
	v_cmp_ne_u32_e32 vcc, v131, v149
	s_and_saveexec_b64 s[18:19], vcc
	s_cbranch_execz .LBB0_750
	v_mul_i32_i24_e32 v50, 0xc00, v131
	v_ashrrev_i32_e32 v51, 31, v50
	v_lshl_add_u64 v[50:51], v[50:51], 2, s[6:7]
	s_mov_b64 s[20:21], 0x2000
	v_lshl_add_u64 v[118:119], v[50:51], 0, s[20:21]
	s_mov_b64 s[20:21], 0xf000
	v_lshl_add_u64 v[110:111], v[50:51], 0, s[20:21]
	v_lshl_add_u64 v[112:113], v[50:51], 0, s[56:57]
	v_mov_b32_e32 v149, v1
	v_mov_b32_e32 v151, v1
	v_lshl_add_u64 v[50:51], v[118:119], 0, v[0:1]
	v_lshl_add_u64 v[70:71], v[110:111], 0, v[0:1]
	v_lshl_add_u64 v[74:75], v[112:113], 0, v[0:1]
	v_lshl_add_u64 v[76:77], v[118:119], 0, v[148:149]
	v_lshl_add_u64 v[98:99], v[110:111], 0, v[148:149]
	v_lshl_add_u64 v[100:101], v[112:113], 0, v[148:149]
	v_lshl_add_u64 v[106:107], v[112:113], 0, v[150:151]
	v_mov_b32_e32 v153, v1
	global_load_dwordx4 v[50:53], v[50:51], off
	s_nop 0
	global_load_dwordx4 v[70:73], v[70:71], off
	s_nop 0
	global_load_dwordx4 v[78:81], v[74:75], off
	s_nop 0
	global_load_dwordx4 v[74:77], v[76:77], off
	s_nop 0
	global_load_dwordx4 v[102:105], v[98:99], off
	s_nop 0
	global_load_dwordx4 v[98:101], v[100:101], off
	v_lshl_add_u64 v[114:115], v[118:119], 0, v[150:151]
	v_lshl_add_u64 v[116:117], v[110:111], 0, v[150:151]
	global_load_dwordx4 v[106:109], v[106:107], off
	v_lshl_add_u64 v[110:111], v[110:111], 0, v[152:153]
	v_lshl_add_u64 v[112:113], v[112:113], 0, v[152:153]
	v_lshl_add_u64 v[118:119], v[118:119], 0, v[152:153]
	global_load_dwordx4 v[126:129], v[110:111], off
	global_load_dwordx4 v[122:125], v[112:113], off
	s_nop 0
	global_load_dwordx4 v[110:113], v[114:115], off
	s_nop 0
	global_load_dwordx4 v[114:117], v[116:117], off
	v_mov_b32_e32 v149, v131
	global_load_dwordx4 v[118:121], v[118:119], off
	s_waitcnt vmcnt(9)
	v_pk_add_f32 v[132:133], v[78:79], 1.0 op_sel_hi:[1,0]
	v_pk_add_f32 v[134:135], v[80:81], 1.0 op_sel_hi:[1,0]
	s_waitcnt vmcnt(6)
	v_pk_add_f32 v[136:137], v[98:99], 1.0 op_sel_hi:[1,0]
	v_pk_add_f32 v[138:139], v[100:101], 1.0 op_sel_hi:[1,0]
	s_waitcnt vmcnt(5)
	v_pk_add_f32 v[140:141], v[106:107], 1.0 op_sel_hi:[1,0]
	v_pk_add_f32 v[142:143], v[108:109], 1.0 op_sel_hi:[1,0]
	s_waitcnt vmcnt(3)
	v_pk_add_f32 v[144:145], v[122:123], 1.0 op_sel_hi:[1,0]
	v_pk_add_f32 v[196:197], v[124:125], 1.0 op_sel_hi:[1,0]
	s_branch .LBB0_750

.LBB0_1304:
	s_or_b64 exec, exec, s[16:17]
	v_mul_f32_e32 v99, v31, v31
	v_fmac_f32_e32 v99, v30, v30
	v_fmac_f32_e32 v99, v32, v32
	v_fmac_f32_e32 v99, v33, v33
	v_fmac_f32_e32 v99, v26, v26
	v_fmac_f32_e32 v99, v27, v27
	v_fmac_f32_e32 v99, v28, v28
	v_fmac_f32_e32 v99, v29, v29
	v_fmac_f32_e32 v99, v22, v22
	v_fmac_f32_e32 v99, v23, v23
	v_fmac_f32_e32 v99, v24, v24
	v_fmac_f32_e32 v99, v25, v25
	v_pk_mul_f32 v[138:139], v[18:19], v[18:19]
	v_pk_mul_f32 v[100:101], v[20:21], v[20:21]
	v_add_f32_e32 v99, v138, v99
	v_add_f32_e32 v99, v139, v99
	v_add_f32_e32 v99, v100, v99
	v_add_f32_e32 v99, v101, v99
	s_nop 1
	v_mov_b32_dpp v100, v99 quad_perm:[1,0,3,2] row_mask:0xf bank_mask:0xf
	v_add_f32_e32 v99, v99, v100
	s_nop 1
	v_mov_b32_dpp v100, v99 quad_perm:[2,3,0,1] row_mask:0xf bank_mask:0xf
	v_add_f32_e32 v99, v99, v100
	s_nop 1
	v_mov_b32_dpp v100, v99 row_half_mirror row_mask:0xf bank_mask:0xf
	v_add_f32_e32 v99, v99, v100
	s_nop 1
	v_mov_b32_dpp v100, v99 row_mirror row_mask:0xf bank_mask:0xf
	v_add_f32_e32 v99, v99, v100
	ds_bpermute_b32 v100, v134, v99
	s_waitcnt lgkmcnt(0)
	v_add_f32_e32 v99, v99, v100
	ds_bpermute_b32 v100, v135, v99
	s_waitcnt lgkmcnt(0)
	v_add_f32_e32 v99, v99, v100
	v_fmamk_f32 v99, v99, 0x3a800000, v207
	v_mul_f32_e32 v100, 0x4b800000, v99
	v_cmp_gt_f32_e32 vcc, s42, v99
	s_nop 1
	v_cndmask_b32_e32 v99, v99, v100, vcc
	v_rsq_f32_e32 v100, v99
	v_ashrrev_i32_e32 v99, 31, v98
	v_lshlrev_b64 v[98:99], 11, v[98:99]
	v_lshl_add_u64 v[98:99], v[122:123], 0, v[98:99]
	v_mul_f32_e32 v101, 0x45800000, v100
	v_cndmask_b32_e32 v100, v100, v101, vcc
	v_pk_mul_f32 v[30:31], v[30:31], v[100:101] op_sel_hi:[1,0]
	v_pk_mul_f32 v[32:33], v[32:33], v[100:101] op_sel_hi:[1,0]
	v_pk_mul_f32 v[18:19], v[18:19], v[100:101] op_sel_hi:[1,0]
	v_pk_mul_f32 v[20:21], v[20:21], v[100:101] op_sel_hi:[1,0]
	v_pk_mul_f32 v[26:27], v[26:27], v[100:101] op_sel_hi:[1,0]
	v_pk_mul_f32 v[28:29], v[28:29], v[100:101] op_sel_hi:[1,0]
	v_pk_mul_f32 v[22:23], v[22:23], v[100:101] op_sel_hi:[1,0]
	v_pk_mul_f32 v[24:25], v[24:25], v[100:101] op_sel_hi:[1,0]
	v_pk_mul_f32 v[30:31], v[2:3], v[30:31]
	v_pk_mul_f32 v[32:33], v[4:5], v[32:33]
	v_pk_mul_f32 v[18:19], v[14:15], v[18:19]
	v_pk_mul_f32 v[20:21], v[16:17], v[20:21]
	v_pk_mul_f32 v[26:27], v[6:7], v[26:27]
	v_pk_mul_f32 v[28:29], v[8:9], v[28:29]
	v_pk_mul_f32 v[22:23], v[10:11], v[22:23]
	v_pk_mul_f32 v[24:25], v[12:13], v[24:25]
	s_waitcnt vmcnt(3)
	v_pk_fma_f32 v[30:31], v[128:129], v[30:31], v[74:75]
	v_pk_fma_f32 v[32:33], v[130:131], v[32:33], v[76:77]
	s_waitcnt vmcnt(0)
	v_pk_fma_f32 v[18:19], v[102:103], v[18:19], v[94:95]
	v_pk_fma_f32 v[20:21], v[104:105], v[20:21], v[96:97]
	v_pk_fma_f32 v[26:27], v[110:111], v[26:27], v[78:79]
	v_pk_fma_f32 v[28:29], v[112:113], v[28:29], v[80:81]
	v_pk_fma_f32 v[22:23], v[106:107], v[22:23], v[90:91]
	v_pk_fma_f32 v[24:25], v[108:109], v[24:25], v[92:93]
	v_cvt_pk_bf16_f32 v30, v30, v31
	v_cvt_pk_bf16_f32 v31, v32, v33
	v_cvt_pk_bf16_f32 v18, v18, v19
	v_cvt_pk_bf16_f32 v19, v20, v21
	v_cvt_pk_bf16_f32 v26, v26, v27
	v_cvt_pk_bf16_f32 v27, v28, v29
	v_cvt_pk_bf16_f32 v22, v22, v23
	v_cvt_pk_bf16_f32 v23, v24, v25
	global_store_dwordx2 v[98:99], v[30:31], off
	global_store_dwordx2 v[98:99], v[26:27], off offset:512
	global_store_dwordx2 v[98:99], v[22:23], off offset:1024
	global_store_dwordx2 v[98:99], v[18:19], off offset:1536

.LBB0_1312:
	s_or_b64 exec, exec, s[14:15]
	s_waitcnt vmcnt(3)
	v_mul_f32_e32 v115, v111, v111
	v_fmac_f32_e32 v115, v110, v110
	v_fmac_f32_e32 v115, v112, v112
	v_fmac_f32_e32 v115, v113, v113
	s_waitcnt vmcnt(2)
	v_fmac_f32_e32 v115, v106, v106
	v_fmac_f32_e32 v115, v107, v107
	v_fmac_f32_e32 v115, v108, v108
	v_fmac_f32_e32 v115, v109, v109
	s_waitcnt vmcnt(1)
	v_fmac_f32_e32 v115, v102, v102
	v_fmac_f32_e32 v115, v103, v103
	v_fmac_f32_e32 v115, v104, v104
	v_fmac_f32_e32 v115, v105, v105
	s_waitcnt vmcnt(0)
	v_pk_mul_f32 v[130:131], v[98:99], v[98:99]
	v_pk_mul_f32 v[128:129], v[100:101], v[100:101]
	v_add_f32_e32 v115, v130, v115
	v_add_f32_e32 v115, v131, v115
	v_add_f32_e32 v115, v128, v115
	v_add_f32_e32 v115, v129, v115
	s_nop 1
	v_mov_b32_dpp v128, v115 quad_perm:[1,0,3,2] row_mask:0xf bank_mask:0xf
	v_pk_add_f32 v[130:131], v[68:69], 1.0 op_sel_hi:[1,0]
	s_movk_i32 s14, 0x6000
	s_waitcnt lgkmcnt(0)
	v_add_f32_e32 v115, v115, v128
	s_nop 1
	v_mov_b32_dpp v128, v115 quad_perm:[2,3,0,1] row_mask:0xf bank_mask:0xf
	s_waitcnt lgkmcnt(0)
	v_add_f32_e32 v115, v115, v128
	s_nop 1
	v_mov_b32_dpp v128, v115 row_half_mirror row_mask:0xf bank_mask:0xf
	s_waitcnt lgkmcnt(0)
	v_add_f32_e32 v115, v115, v128
	s_nop 1
	v_mov_b32_dpp v128, v115 row_mirror row_mask:0xf bank_mask:0xf
	s_waitcnt lgkmcnt(0)
	v_add_f32_e32 v115, v115, v128
	ds_bpermute_b32 v128, v134, v115
	s_waitcnt lgkmcnt(0)
	v_add_f32_e32 v115, v115, v128
	ds_bpermute_b32 v128, v135, v115
	s_waitcnt lgkmcnt(0)
	v_add_f32_e32 v115, v115, v128
	v_fmamk_f32 v115, v115, 0x3a800000, v207
	v_cmp_gt_f32_e32 vcc, s42, v115
	v_mul_f32_e32 v128, 0x4b800000, v115
	s_nop 0
	v_cndmask_b32_e32 v115, v115, v128, vcc
	v_rsq_f32_e32 v115, v115
	s_nop 0
	v_mul_f32_e32 v128, 0x45800000, v115
	v_cndmask_b32_e32 v132, v115, v128, vcc
	v_pk_mul_f32 v[110:111], v[110:111], v[132:133] op_sel_hi:[1,0]
	v_pk_mul_f32 v[112:113], v[112:113], v[132:133] op_sel_hi:[1,0]
	v_pk_add_f32 v[128:129], v[66:67], 1.0 op_sel_hi:[1,0]
	v_pk_mul_f32 v[110:111], v[2:3], v[110:111]
	v_pk_mul_f32 v[112:113], v[4:5], v[112:113]
	v_pk_fma_f32 v[110:111], v[128:129], v[110:111], v[74:75]
	v_pk_fma_f32 v[112:113], v[130:131], v[112:113], v[76:77]
	v_cvt_pk_bf16_f32 v110, v110, v111
	v_cvt_pk_bf16_f32 v111, v112, v113
	v_pk_mul_f32 v[106:107], v[106:107], v[132:133] op_sel_hi:[1,0]
	v_pk_mul_f32 v[108:109], v[108:109], v[132:133] op_sel_hi:[1,0]
	global_store_dwordx2 v[124:125], v[110:111], off offset:-1024
	v_pk_add_f32 v[110:111], v[70:71], 1.0 op_sel_hi:[1,0]
	v_pk_add_f32 v[112:113], v[72:73], 1.0 op_sel_hi:[1,0]
	v_pk_mul_f32 v[106:107], v[6:7], v[106:107]
	v_pk_mul_f32 v[108:109], v[8:9], v[108:109]
	v_pk_fma_f32 v[106:107], v[110:111], v[106:107], v[78:79]
	v_pk_fma_f32 v[108:109], v[112:113], v[108:109], v[80:81]
	v_cvt_pk_bf16_f32 v106, v106, v107
	v_cvt_pk_bf16_f32 v107, v108, v109
	v_pk_mul_f32 v[102:103], v[102:103], v[132:133] op_sel_hi:[1,0]
	v_pk_mul_f32 v[104:105], v[104:105], v[132:133] op_sel_hi:[1,0]
	global_store_dwordx2 v[124:125], v[106:107], off offset:-512
	v_pk_add_f32 v[106:107], v[82:83], 1.0 op_sel_hi:[1,0]
	v_pk_add_f32 v[108:109], v[84:85], 1.0 op_sel_hi:[1,0]
	v_pk_mul_f32 v[102:103], v[10:11], v[102:103]
	v_pk_mul_f32 v[104:105], v[12:13], v[104:105]
	v_pk_fma_f32 v[102:103], v[106:107], v[102:103], v[90:91]
	v_pk_fma_f32 v[104:105], v[108:109], v[104:105], v[92:93]
	v_cvt_pk_bf16_f32 v102, v102, v103
	v_cvt_pk_bf16_f32 v103, v104, v105
	v_pk_mul_f32 v[98:99], v[98:99], v[132:133] op_sel_hi:[1,0]
	v_pk_mul_f32 v[100:101], v[100:101], v[132:133] op_sel_hi:[1,0]
	global_store_dwordx2 v[124:125], v[102:103], off
	v_pk_add_f32 v[102:103], v[86:87], 1.0 op_sel_hi:[1,0]
	v_pk_add_f32 v[104:105], v[88:89], 1.0 op_sel_hi:[1,0]
	v_pk_mul_f32 v[98:99], v[14:15], v[98:99]
	v_pk_mul_f32 v[100:101], v[16:17], v[100:101]
	v_pk_fma_f32 v[98:99], v[102:103], v[98:99], v[94:95]
	v_pk_fma_f32 v[100:101], v[104:105], v[100:101], v[96:97]
	v_cvt_pk_bf16_f32 v98, v98, v99
	v_cvt_pk_bf16_f32 v99, v100, v101
	global_store_dwordx2 v[124:125], v[98:99], off offset:512
	v_add_u32_e32 v98, s18, v114
	v_cmp_gt_i32_e32 vcc, s14, v98
	s_and_saveexec_b64 s[14:15], vcc
	s_cbranch_execz .LBB0_1305
	v_add_u32_e32 v99, 0xffffe000, v98
	v_ashrrev_i32_e32 v99, 12, v99
	v_add_u32_e32 v99, 1, v99
	v_cmp_lt_i32_e32 vcc, s43, v98
	s_nop 1
	v_cndmask_b32_e32 v99, 0, v99, vcc
	v_cmp_ne_u32_e32 vcc, v99, v136
	s_and_saveexec_b64 s[16:17], vcc
	s_cbranch_execz .LBB0_1304
	v_mul_i32_i24_e32 v66, 0xc00, v99
	v_ashrrev_i32_e32 v67, 31, v66
	v_lshl_add_u64 v[66:67], v[66:67], 2, s[6:7]
	v_lshl_add_u64 v[74:75], v[66:67], 0, s[44:45]
	v_lshlrev_b32_e32 v68, 2, v116
	v_mov_b32_e32 v69, v1
	v_lshl_add_u64 v[94:95], v[66:67], 0, v[0:1]
	v_lshl_add_u64 v[66:67], v[74:75], 0, v[0:1]
	v_lshl_add_u64 v[70:71], v[74:75], 0, v[68:69]
	global_load_dwordx4 v[66:69], v[66:67], off
	s_nop 0
	global_load_dwordx4 v[70:73], v[70:71], off
	v_lshlrev_b32_e32 v76, 2, v118
	v_mov_b32_e32 v77, v1
	v_lshlrev_b32_e32 v78, 2, v120
	v_mov_b32_e32 v79, v1
	v_lshl_add_u64 v[76:77], v[74:75], 0, v[76:77]
	v_lshl_add_u64 v[74:75], v[74:75], 0, v[78:79]
	global_load_dwordx4 v[82:85], v[76:77], off
	global_load_dwordx4 v[86:89], v[74:75], off
	s_nop 0
	global_load_dwordx4 v[74:77], v[94:95], off
	global_load_dwordx4 v[78:81], v[94:95], off offset:1024
	global_load_dwordx4 v[90:93], v[94:95], off offset:2048
	s_nop 0
	global_load_dwordx4 v[94:97], v[94:95], off offset:3072
	v_mov_b32_e32 v136, v99
	s_waitcnt vmcnt(7)
	v_pk_add_f32 v[128:129], v[66:67], 1.0 op_sel_hi:[1,0]
	v_pk_add_f32 v[130:131], v[68:69], 1.0 op_sel_hi:[1,0]
	s_waitcnt vmcnt(6)
	v_pk_add_f32 v[110:111], v[70:71], 1.0 op_sel_hi:[1,0]
	v_pk_add_f32 v[112:113], v[72:73], 1.0 op_sel_hi:[1,0]
	s_waitcnt vmcnt(5)
	v_pk_add_f32 v[106:107], v[82:83], 1.0 op_sel_hi:[1,0]
	v_pk_add_f32 v[108:109], v[84:85], 1.0 op_sel_hi:[1,0]
	s_waitcnt vmcnt(4)
	v_pk_add_f32 v[102:103], v[86:87], 1.0 op_sel_hi:[1,0]
	v_pk_add_f32 v[104:105], v[88:89], 1.0 op_sel_hi:[1,0]
	s_branch .LBB0_1304
